# v55 plus the same group-size hard-coding in the w_in and N=2048 GEMM tile-index code
# baseline (speedup 1.0000x reference)
;     __host__ __device__ bool next(int i, Unit& u) const {
;         const long L = (long)i * G + c; if (L >= nwg) return false;
;         int wgid = (int)L; { const int q = nwg / NXCD, r = nwg % NXCD, xcd = wgid % NXCD, off = wgid / NXCD; wgid = (xcd < r ? xcd * (q + 1) : r * (q + 1) + (xcd - r) * q) + off; }
;         const int nig = wgm * nN, gid = wgid / nig, fm = gid * wgm, gsz = (nM - fm) < wgm ? (nM - fm) : wgm;
;         u.pm = fm + ((wgid % nig) % gsz); u.pn = (wgid % nig) / gsz; return true;
.LBB0_307:
	s_add_i32 s47, s47, 1
	s_mul_i32 s6, s47, s67
	s_mul_hi_u32 s7, s47, s26
	s_add_i32 s7, s7, s6
	s_mul_i32 s6, s47, s26
	s_add_u32 s6, s6, s2
	s_addc_u32 s7, s7, s33
	v_mov_b64_e32 v[2:3], 0x500
	v_cmp_lt_i64_e64 s[8:9], s[6:7], v[2:3]
	v_mov_b64_e32 v[2:3], 0x4ff
	v_cmp_gt_i64_e32 vcc, s[6:7], v[2:3]
	s_cbranch_vccnz .LBB0_309
	s_ashr_i32 s7, s6, 31
	s_lshr_b32 s7, s7, 29
	s_add_i32 s7, s6, s7
	s_ashr_i32 s14, s7, 3
	s_and_b32 s7, s7, -8
	s_sub_i32 s6, s6, s7
	s_cmp_lt_i32 s6, 0
	s_movk_i32 s7, 0xa1
	s_cselect_b32 s7, s7, 0xa0
	s_mul_i32 s6, s7, s6
	s_add_i32 s6, s6, s14
	s_mul_hi_i32 s7, s6, 0x66666667
	s_lshr_b32 s14, s7, 31
	s_ashr_i32 s7, s7, 6
	s_add_i32 s7, s7, s14
	s_lshl_b32 s14, s7, 3
	s_mulk_i32 s7, 0xa0
	s_sub_i32 s6, s6, s7
	s_lshr_b32 s31, s6, 3
	s_and_b32 s6, s6, 7
	s_add_i32 s20, s6, s14

;     __host__ __device__ bool next(int i, Unit& u) const {
;         const long L = (long)i * G + c; if (L >= nwg) return false;
;         int wgid = (int)L; { const int q = nwg / NXCD, r = nwg % NXCD, xcd = wgid % NXCD, off = wgid / NXCD; wgid = (xcd < r ? xcd * (q + 1) : r * (q + 1) + (xcd - r) * q) + off; }
;         const int nig = wgm * nN, gid = wgid / nig, fm = gid * wgm, gsz = (nM - fm) < wgm ? (nM - fm) : wgm;
;         u.pm = fm + ((wgid % nig) % gsz); u.pn = (wgid % nig) / gsz; return true;
.LBB0_374:
	s_ashr_i32 s4, s6, 3
	s_add_i32 s4, s18, s4
	s_ashr_i32 s5, s4, 31
	s_lshr_b32 s5, s5, 27
	s_add_i32 s5, s4, s5
	s_ashr_i32 s6, s5, 5
	s_lshl_b32 s6, s6, 2
	s_andn2_b32 s5, s5, 31
	s_sub_i32 s4, s4, s5
	s_lshr_b32 s20, s4, 2
	s_and_b32 s4, s4, 3
	s_add_i32 s31, s6, s4
